# v66 + out-proj phase (s6): bulk L2 prefetch of the first 8 K-tiles of the workgroup's A and B panels issued ahead of the first LDS-DMA loads
# speedup vs baseline: 1.0061x; 1.0009x over previous
.LBB0_64:
	s_and_b64 vcc, exec, s[0:1]
	s_cbranch_vccnz .LBB0_125
	v_ashrrev_i32_e32 v1, 31, v14
	v_lshrrev_b32_e32 v1, 26, v1
	v_add_u32_e32 v1, v14, v1
	v_ashrrev_i32_e32 v8, 6, v1
	v_bfe_i32 v1, v14, 27, 1
	v_lshlrev_b32_e32 v0, 4, v14
	v_lshrrev_b32_e32 v1, 22, v1
	v_add_u32_e32 v1, v0, v1
	v_and_b32_e32 v1, 0xfffffc00, v1
	v_sub_u32_e32 v1, v0, v1
	v_lshrrev_b32_e32 v2, 4, v1
	v_bitop3_b32 v2, v2, v1, 32 bitop3:0x6c
	v_ashrrev_i32_e32 v1, 31, v1
	v_lshrrev_b32_e32 v1, 26, v1
	v_add_u32_e32 v1, v2, v1
	v_ashrrev_i32_e32 v9, 6, v1
	v_mul_i32_i24_e32 v4, 64, v9
	v_sub_u32_e32 v2, v2, v4
	v_lshlrev_b32_e32 v3, 3, v8
	v_lshlrev_b32_e32 v1, 5, v8
	v_ashrrev_i16_sdwa v2, v239, sext(v2) dst_sel:DWORD dst_unused:UNUSED_PAD src0_sel:DWORD src1_sel:BYTE_0
	v_and_b32_e32 v3, 0x1ffff0, v3
	v_and_b32_e32 v1, 32, v1
	v_bfe_i32 v10, v2, 0, 16
	v_add_u32_e32 v1, v1, v10
	v_add_lshl_u32 v2, v9, v3, 11
	v_add_u32_e32 v0, 0x2000, v0
	s_waitcnt vmcnt(0)
	v_lshl_add_u32 v194, v1, 1, v2
	v_ashrrev_i32_e32 v1, 31, v0
	v_lshrrev_b32_e32 v1, 22, v1
	v_add_u32_e32 v1, v0, v1
	v_ashrrev_i32_e32 v11, 10, v1
	v_mul_i32_i24_e32 v1, 0x400, v11
	v_sub_u32_e32 v0, v0, v1
	v_readlane_b32 s0, v254, 28
	v_lshrrev_b32_e32 v1, 4, v0
	v_readlane_b32 s1, v254, 29
	s_add_u32 s13, s0, 0x8e00000
	v_bitop3_b32 v0, v1, v0, 32 bitop3:0x6c
	s_addc_u32 s12, s1, 0
	v_readlane_b32 s0, v255, 9
	v_ashrrev_i32_e32 v2, 31, v0
	s_add_u32 s10, s0, 0xc80000
	v_readlane_b32 s0, v255, 10
	v_lshrrev_b32_e32 v2, 26, v2
	s_addc_u32 s11, s0, 0
	s_ashr_i32 s0, s9, 6
	v_add_u32_e32 v2, v0, v2
	s_ashr_i32 s29, s28, 31
	s_ashr_i32 s39, s38, 31
	v_ashrrev_i32_e32 v12, 6, v2
	v_and_b32_e32 v2, 0xc0, v2
	s_ashr_i32 s1, s9, 8
	s_lshl_b32 s52, s0, 10
	s_lshl_b64 s[2:3], s[28:29], 18
	s_lshl_b64 s[4:5], s[38:39], 19
	v_sub_u32_e32 v0, v0, v2
	s_add_u32 s4, s10, s4
	v_lshlrev_b32_e32 v1, 3, v11
	v_lshlrev_b32_e32 v3, 5, v11
	v_ashrrev_i16_sdwa v0, v239, sext(v0) dst_sel:DWORD dst_unused:UNUSED_PAD src0_sel:DWORD src1_sel:BYTE_0
	s_addc_u32 s5, s11, s5
	s_add_i32 s44, s52, 16
	v_and_b32_e32 v1, 0x1ffff0, v1
	v_and_b32_e32 v3, 32, v3
	v_bfe_i32 v13, v0, 0, 16
	s_add_i32 m0, s44, 0x10000
	v_add_u32_e32 v0, v3, v13
	v_add_lshl_u32 v1, v12, v1, 11
	v_and_b32_e32 v126, 0xff, v236
	v_lshrrev_b32_e32 v127, 8, v236
	v_lshlrev_b32_e32 v126, 11, v126
	v_lshl_or_b32 v126, v127, 9, v126
	s_add_u32 s98, s13, s2
	s_addc_u32 s99, s12, s3
	global_load_dword v127, v126, s[98:99]
	global_load_dword v127, v126, s[98:99] offset:128
	global_load_dword v127, v126, s[98:99] offset:256
	global_load_dword v127, v126, s[98:99] offset:384
	global_load_dword v127, v126, s[4:5]
	global_load_dword v127, v126, s[4:5] offset:128
	global_load_dword v127, v126, s[4:5] offset:256
	global_load_dword v127, v126, s[4:5] offset:384
	global_load_lds_dwordx4 v194, s[4:5]
	s_add_i32 m0, s44, 0x12000
	v_lshl_add_u32 v196, v0, 1, v1
	v_writelane_b32 v255, s10, 13
	s_add_u32 s10, s4, 0x40000
	v_writelane_b32 v255, s11, 26
	global_load_lds_dwordx4 v196, s[4:5]
	s_addc_u32 s11, s5, 0
	s_add_i32 m0, s44, 0x14000
	v_writelane_b32 v255, s13, 24
	global_load_lds_dwordx4 v194, s[10:11]
	s_add_i32 m0, s44, 0x16000
	s_add_u32 s2, s13, s2
	s_addc_u32 s3, s12, s3
	s_add_i32 s45, s44, 0x2000
	global_load_lds_dwordx4 v196, s[10:11]
	s_mov_b32 m0, s44
	s_add_u32 s6, s2, s6
	global_load_lds_dwordx4 v194, s[2:3]
	s_mov_b32 m0, s45
	s_addc_u32 s7, s3, s7
	s_add_i32 s30, s44, 0x4000
	global_load_lds_dwordx4 v196, s[2:3]
	s_mov_b32 m0, s30
	s_add_i32 s31, s44, 0x6000
	global_load_lds_dwordx4 v194, s[6:7]
	s_mov_b32 m0, s31
	s_cmp_eq_u32 s1, 1
	global_load_lds_dwordx4 v196, s[6:7]
	v_writelane_b32 v255, s12, 40
	s_cselect_b64 s[6:7], -1, 0
	v_mov_b32_e32 v195, v161
	v_mov_b32_e32 v197, v161
	v_writelane_b32 v255, s6, 41
	v_lshl_add_u64 v[6:7], s[4:5], 0, v[194:195]
	v_lshl_add_u64 v[4:5], s[4:5], 0, v[196:197]
	v_lshl_add_u64 v[0:1], s[2:3], 0, v[194:195]
	v_writelane_b32 v255, s7, 42
	s_cmp_lg_u32 s1, 1
	v_lshl_add_u64 v[2:3], s[2:3], 0, v[196:197]
	s_cbranch_scc1 .LBB0_67
	s_barrier
